# nt cache-policy hint on the scan wave's once-read operand loads and state-snapshot stores
# baseline (speedup 1.0000x reference)
; #define LAS __attribute__((address_space(3)))
; DI f32x16 zero16() { f32x16 z; for (int i = 0; i < 16; ++i) z[i] = 0.f; return z; }
; DI void phase_scan(KArgs args, LAS unsigned char* L, const Ctx& c) {
;     ...
;     const int nwu = c.nseq * 24, wu = c.bid;
;     if (wu < nwu && c.wave == 0) {
;         const int lane = c.lane;
;         const int chain = wu >> 1, nt = wu & 1, seq = chain / 12, rem = chain % 12, head = rem >> 1, dir = rem & 1;
;         const int nch = c.seqlen >> 6, gch0 = seq * nch;
;         unsigned char* GS = BIGP(unsigned char, B_GSCR);
;         f32x16 S[2]; S[0] = zero16(); S[1] = zero16();
;         bf16x8 A[2][2][4]; u32x4 cm[2][2][2];
;         const long gstep = (long)(dir ? -1 : 1) * 12 * GSTRIDE;
;         const unsigned char* G0 = GS + (size_t)(((gch0 + (dir ? nch - 1 : 0)) * 6 + head) * 2 + dir) * GSTRIDE;
;         unsigned char* Gs = (unsigned char*)G0;
;         float glv[4];
; #pragma unroll
;         for (int q = 0; q < 4; ++q) { const int sq = q * 64 + lane; glv[q] = *(const float*)(G0 + (long)(sq < nch ? sq : nch - 1) * gstep + 40960); }
;         LAS unsigned char* RING = L + 81920;
;         int dslot = 0, rslot = 0, dstage = 0;
;     ...
;         SCAN_DMA(); SCAN_DMA(); SCAN_DMA(); SCAN_DMA(); SCAN_DMA();
;         asm volatile("s_waitcnt vmcnt(48)" ::: "memory"); SCAN_LOAD(0);
;         asm volatile("s_waitcnt vmcnt(36)" ::: "memory"); SCAN_LOAD(1);
.LBB0_646:
	s_movk_i32 s33, 0x600
	s_and_b64 vcc, exec, s[0:1]
	s_cbranch_vccz .LBB0_946
	v_readlane_b32 s2, v254, 23
	s_lshr_b32 s30, s60, 6
	v_readlane_b32 s3, v254, 24
	s_and_b64 s[0:1], s[2:3], exec
	s_cselect_b32 s0, 6, 8
	s_add_i32 s31, s30, -1
	v_writelane_b32 v254, s0, 32
	s_and_b64 s[0:1], s[2:3], exec
	s_cselect_b32 s2, 0xc0, 24
	s_cmp_lt_u32 s61, 64
	s_cselect_b64 s[0:1], -1, 0
	s_cmp_lt_i32 s68, s2
	s_cselect_b64 s[2:3], -1, 0
	s_and_b64 s[0:1], s[2:3], s[0:1]
	s_andn2_b64 vcc, exec, s[0:1]
	s_movk_i32 s27, 0x90
	v_readlane_b32 s28, v254, 27
	v_readlane_b32 s29, v254, 29
	s_cbranch_vccnz .LBB0_651
	s_setprio 3
	s_ashr_i32 s0, s68, 1
	s_mul_hi_i32 s1, s0, 0x2aaaaaab
	s_lshr_b32 s2, s1, 31
	s_ashr_i32 s1, s1, 1
	s_add_i32 s1, s1, s2
	s_mul_i32 s2, s1, 12
	s_sub_i32 s2, s0, s2
	v_readlane_b32 s4, v254, 32
	s_bfe_i32 s3, s2, 0x10000
	s_and_b32 s0, s2, 1
	s_lshl_b32 s4, s1, s4
	s_cmp_eq_u32 s0, 0
	s_mov_b32 s0, 0x78c00
	s_cselect_b32 s1, 0, -1
	s_cselect_b32 s0, s0, 0xfff87400
	s_and_b32 s3, s3, s31
	s_add_i32 s3, s3, s4
	s_mul_i32 s3, s3, 12
	s_add_i32 s24, s3, s2
	s_mul_hi_i32 s23, s24, 0xa100
	s_mul_i32 s24, s24, 0xa100
	s_waitcnt lgkmcnt(0)
	s_add_u32 s6, s72, s24
	s_addc_u32 s7, s73, s23
	s_add_u32 s2, s6, 0x37800000
	s_addc_u32 s3, s7, 0
	v_min_i32_e32 v1, s31, v28
	v_mov_b64_e32 v[4:5], s[2:3]
	v_mad_u64_u32 v[6:7], s[4:5], s0, v1, v[4:5]
	v_mad_i32_i24 v1, s1, v1, v7
	v_or_b32_e32 v7, 64, v28
	v_min_i32_e32 v2, s31, v7
	v_mad_u64_u32 v[8:9], s[4:5], s0, v2, v[4:5]
	v_or_b32_e32 v12, 0x80, v28
	v_mad_i32_i24 v9, s1, v2, v9
	v_min_i32_e32 v2, s31, v12
	v_mad_u64_u32 v[10:11], s[4:5], s0, v2, v[4:5]
	v_or_b32_e32 v13, 0xc0, v28
	v_mad_i32_i24 v11, s1, v2, v11
	v_min_i32_e32 v2, s31, v13
	v_mad_u64_u32 v[4:5], s[4:5], s0, v2, v[4:5]
	s_add_u32 s20, s6, 0x37802000
	s_addc_u32 s21, s7, 0
	s_lshl_b32 s4, s68, 12
	s_and_b32 s25, s4, 0x1000
	s_add_u32 s18, s2, s0
	s_addc_u32 s19, s3, s1
	s_add_u32 s16, s18, 0x2000
	s_addc_u32 s17, s19, 0
	s_add_u32 s14, s18, s0
	s_addc_u32 s15, s19, s1
	s_add_u32 s12, s14, 0x2000
	s_addc_u32 s13, s15, 0
	s_add_u32 s10, s14, s0
	s_addc_u32 s11, s15, s1
	s_mov_b32 s26, 0xa000
	s_add_u32 s8, s10, 0x2000
	v_add_co_u32_e32 v6, vcc, s26, v6
	v_lshlrev_b32_e32 v148, 4, v7
	s_addc_u32 s9, s11, 0
	v_addc_co_u32_e32 v7, vcc, 0, v1, vcc
	s_add_u32 s6, s10, s0
	v_add_co_u32_e32 v8, vcc, s26, v8
	s_addc_u32 s7, s11, s1
	s_nop 0
	v_addc_co_u32_e32 v9, vcc, 0, v9, vcc
	s_add_u32 s4, s6, 0x2000
	v_add_co_u32_e32 v10, vcc, s26, v10
	s_addc_u32 s5, s7, 0
	s_add_i32 s22, 0, 0x14000
	v_addc_co_u32_e32 v11, vcc, 0, v11, vcc
	v_mad_i32_i24 v5, s1, v2, v5
	v_lshlrev_b32_e32 v2, 4, v28
	v_add_co_u32_e32 v4, vcc, s26, v4
	v_addc_co_u32_e32 v5, vcc, 0, v5, vcc
	global_load_dword v1, v[6:7], off
	global_load_dword v168, v[8:9], off
	global_load_dword v169, v[10:11], off
	global_load_dword v170, v[4:5], off
	v_lshlrev_b32_e32 v150, 4, v12
	v_lshlrev_b32_e32 v152, 4, v13
	v_or_b32_e32 v154, 0x1000, v2
	v_or_b32_e32 v156, 0x1400, v2
	v_or_b32_e32 v158, 0x1800, v2
	v_or_b32_e32 v160, 0x1c00, v2
	v_lshl_or_b32 v162, v28, 5, s25
	v_mov_b32_e32 v163, v3
	v_lshl_add_u64 v[12:13], s[20:21], 0, v[162:163]
	v_lshl_add_u64 v[12:13], v[12:13], 0, 16
	v_or_b32_e32 v164, 0x800, v162
	v_mov_b32_e32 v165, v3
	v_lshl_add_u64 v[14:15], s[20:21], 0, v[164:165]
	v_lshl_add_u64 v[14:15], v[14:15], 0, 16
	v_lshl_add_u64 v[16:17], s[16:17], 0, v[162:163]
	v_lshl_add_u64 v[16:17], v[16:17], 0, 16
	v_lshl_add_u64 v[18:19], s[16:17], 0, v[164:165]
	v_lshl_add_u64 v[18:19], v[18:19], 0, 16
	v_lshl_add_u64 v[20:21], s[12:13], 0, v[162:163]
	v_lshl_add_u64 v[20:21], v[20:21], 0, 16
	v_lshl_add_u64 v[22:23], s[12:13], 0, v[164:165]
	v_lshl_add_u64 v[22:23], v[22:23], 0, 16
	v_lshl_add_u64 v[24:25], s[8:9], 0, v[162:163]
	v_lshl_add_u64 v[24:25], v[24:25], 0, 16
	v_lshl_add_u64 v[26:27], s[8:9], 0, v[164:165]
	v_lshl_add_u64 v[26:27], v[26:27], 0, 16
	v_lshl_add_u64 v[28:29], s[4:5], 0, v[162:163]
	v_lshl_add_u64 v[28:29], v[28:29], 0, 16
	v_lshl_add_u64 v[30:31], s[4:5], 0, v[164:165]
	v_lshl_add_u64 v[30:31], v[30:31], 0, 16
	s_add_u32 s4, s24, s25
	s_addc_u32 s5, s23, 0
	s_add_u32 s4, s72, s4
	s_addc_u32 s5, s73, s5
	v_lshl_add_u64 v[4:5], s[4:5], 0, v[2:3]
	s_mov_b64 s[4:5], 0x37808800
	v_lshl_add_u64 v[166:167], v[4:5], 0, s[4:5]
	v_mov_b32_e32 v4, 0
	v_mov_b32_e32 v149, v3
	v_mov_b32_e32 v151, v3
	v_mov_b32_e32 v153, v3
	v_mov_b32_e32 v155, v3
	v_mov_b32_e32 v157, v3
	v_mov_b32_e32 v159, v3
	v_mov_b32_e32 v161, v3
	s_lshl_b64 s[8:9], s[0:1], 1
	v_mov_b32_e32 v5, v4
	v_mov_b32_e32 v6, v4
	v_mov_b32_e32 v7, v4
	v_mov_b32_e32 v8, v4
	v_mov_b32_e32 v9, v4
	v_mov_b32_e32 v10, v4
	v_mov_b32_e32 v11, v4
	v_mov_b32_e32 v12, v4
	v_mov_b32_e32 v13, v4
	v_mov_b32_e32 v14, v4
	v_mov_b32_e32 v15, v4
	v_mov_b32_e32 v16, v4
	v_mov_b32_e32 v17, v4
	v_mov_b32_e32 v18, v4
	v_mov_b32_e32 v19, v4
	v_mov_b32_e32 v20, v4
	v_mov_b32_e32 v21, v4
	v_mov_b32_e32 v22, v4
	v_mov_b32_e32 v23, v4
	v_mov_b32_e32 v24, v4
	v_mov_b32_e32 v25, v4
	v_mov_b32_e32 v26, v4
	v_mov_b32_e32 v27, v4
	v_mov_b32_e32 v28, v4
	v_mov_b32_e32 v29, v4
	v_mov_b32_e32 v30, v4
	v_mov_b32_e32 v31, v4
	v_mov_b32_e32 v32, v4
	v_mov_b32_e32 v33, v4
	v_mov_b32_e32 v34, v4
	v_mov_b32_e32 v35, v4
	s_mov_b64 s[12:13], s[2:3]
	s_mov_b32 s11, 0
	s_mov_b32 s10, 0
	s_add_u32 s14, s12, 0x1000
	s_addc_u32 s15, s13, 0
	s_add_u32 s16, s12, 0x2000
	s_addc_u32 s17, s13, 0
	global_load_dwordx4 v[36:39], v2, s[12:13] nt
	global_load_dwordx4 v[40:43], v2, s[12:13] offset:1024 nt
	global_load_dwordx4 v[44:47], v2, s[12:13] offset:2048 nt
	global_load_dwordx4 v[48:51], v2, s[12:13] offset:3072 nt
	global_load_dwordx4 v[52:55], v2, s[14:15] nt
; DI void phase_scan(KArgs args, LAS unsigned char* L, const Ctx& c) {
;     ...
;         SCAN_DMA(); SCAN_DMA(); SCAN_DMA(); SCAN_DMA(); SCAN_DMA();
;         asm volatile("s_waitcnt vmcnt(48)" ::: "memory"); SCAN_LOAD(0);
;         asm volatile("s_waitcnt vmcnt(36)" ::: "memory"); SCAN_LOAD(1);
;         for (int step = 0; step < nch; step += 2) {
;             SCAN_STEP(0, step);     asm volatile("s_waitcnt vmcnt(24)" ::: "memory"); SCAN_LOAD(0); SCAN_DMA();
;             SCAN_STEP(1, step + 1); asm volatile("s_waitcnt vmcnt(24)" ::: "memory"); SCAN_LOAD(1); SCAN_DMA();
	global_load_dwordx4 v[56:59], v2, s[14:15] offset:1024 nt
	global_load_dwordx4 v[60:63], v2, s[14:15] offset:2048 nt
	global_load_dwordx4 v[64:67], v2, s[14:15] offset:3072 nt
	global_load_dwordx4 v[68:71], v162, s[16:17] nt
	global_load_dwordx4 v[72:75], v162, s[16:17] offset:16 nt
	global_load_dwordx4 v[76:79], v164, s[16:17] nt
	global_load_dwordx4 v[80:83], v164, s[16:17] offset:16 nt
	s_add_i32 s11, s11, 1
	s_cmp_le_u32 s11, s31
	s_cselect_b32 s6, s0, 0
	s_cselect_b32 s7, s1, 0
	s_add_u32 s12, s12, s6
	s_addc_u32 s13, s13, s7
	s_add_u32 s14, s12, 0x1000
	s_addc_u32 s15, s13, 0
	s_add_u32 s16, s12, 0x2000
	s_addc_u32 s17, s13, 0
	global_load_dwordx4 v[84:87], v2, s[12:13] nt
	global_load_dwordx4 v[88:91], v2, s[12:13] offset:1024 nt
	global_load_dwordx4 v[92:95], v2, s[12:13] offset:2048 nt
	global_load_dwordx4 v[96:99], v2, s[12:13] offset:3072 nt
	global_load_dwordx4 v[100:103], v2, s[14:15] nt
	global_load_dwordx4 v[104:107], v2, s[14:15] offset:1024 nt
	global_load_dwordx4 v[108:111], v2, s[14:15] offset:2048 nt
	global_load_dwordx4 v[112:115], v2, s[14:15] offset:3072 nt
	global_load_dwordx4 v[116:119], v162, s[16:17] nt
	global_load_dwordx4 v[120:123], v162, s[16:17] offset:16 nt
	global_load_dwordx4 v[124:127], v164, s[16:17] nt
	global_load_dwordx4 v[128:131], v164, s[16:17] offset:16 nt
	s_add_i32 s11, s11, 1
	s_cmp_le_u32 s11, s31
	s_cselect_b32 s6, s0, 0
	s_cselect_b32 s7, s1, 0
	s_add_u32 s12, s12, s6
	s_addc_u32 s13, s13, s7
	s_add_u32 s14, s12, 0x1000
	s_addc_u32 s15, s13, 0
	s_add_u32 s16, s12, 0x2000
	s_addc_u32 s17, s13, 0
	global_load_dwordx4 v[178:181], v2, s[12:13] nt
	global_load_dwordx4 v[182:185], v2, s[12:13] offset:1024 nt
	global_load_dwordx4 v[186:189], v2, s[12:13] offset:2048 nt
	global_load_dwordx4 v[190:193], v2, s[12:13] offset:3072 nt
	global_load_dwordx4 v[194:197], v2, s[14:15] nt
	global_load_dwordx4 v[198:201], v2, s[14:15] offset:1024 nt
	global_load_dwordx4 v[202:205], v2, s[14:15] offset:2048 nt
	global_load_dwordx4 v[226:229], v2, s[14:15] offset:3072 nt
	global_load_dwordx4 v[230:233], v162, s[16:17] nt
	global_load_dwordx4 v[234:237], v162, s[16:17] offset:16 nt
	global_load_dwordx4 v[238:241], v164, s[16:17] nt
	global_load_dwordx4 v[242:245], v164, s[16:17] offset:16 nt
	s_add_i32 s11, s11, 1
	s_cmp_le_u32 s11, s31
	s_cselect_b32 s6, s0, 0
	s_cselect_b32 s7, s1, 0
	s_add_u32 s12, s12, s6
	s_addc_u32 s13, s13, s7
	s_waitcnt vmcnt(12)
.Lscan_loop:
	s_waitcnt vmcnt(32)
	s_lshr_b32 s6, s10, 6
	s_cmp_lt_u32 s10, 64
	s_cselect_b64 vcc, -1, 0
	s_cmp_eq_u32 s6, 1
	s_cselect_b64 s[4:5], -1, 0
	s_cmp_eq_u32 s6, 2
	s_cselect_b64 s[6:7], -1, 0
	v_cndmask_b32_e64 v172, v170, v169, s[6:7]
	v_cndmask_b32_e64 v172, v172, v168, s[4:5]
	v_cndmask_b32_e32 v172, v172, v1, vcc
	v_cvt_pk_bf16_f32 v132, v4, v5
	v_cvt_pk_bf16_f32 v133, v6, v7
	v_cvt_pk_bf16_f32 v134, v8, v9
	v_cvt_pk_bf16_f32 v135, v10, v11
	v_cvt_pk_bf16_f32 v136, v12, v13
	v_cvt_pk_bf16_f32 v137, v14, v15
	v_cvt_pk_bf16_f32 v138, v16, v17
	v_cvt_pk_bf16_f32 v139, v18, v19
	v_cvt_pk_bf16_f32 v140, v20, v21
	v_cvt_pk_bf16_f32 v141, v22, v23
	v_cvt_pk_bf16_f32 v142, v24, v25
	v_cvt_pk_bf16_f32 v143, v26, v27
	v_cvt_pk_bf16_f32 v144, v28, v29
	v_cvt_pk_bf16_f32 v145, v30, v31
	v_cvt_pk_bf16_f32 v146, v32, v33
	v_cvt_pk_bf16_f32 v147, v34, v35
	v_readlane_b32 s4, v172, s10
	global_store_dwordx4 v[166:167], v[132:135], off offset:-2048 nt
	global_store_dwordx4 v[166:167], v[136:139], off offset:-1024 nt
	global_store_dwordx4 v[166:167], v[140:143], off nt
	global_store_dwordx4 v[166:167], v[144:147], off offset:1024 nt
	v_lshlrev_b32_e32 v174, 16, v68
	v_and_b32_e32 v175, 0xffff0000, v68
	v_pk_fma_f32 v[4:5], v[4:5], s[4:5], v[174:175] op_sel_hi:[1,0,1]
	v_lshlrev_b32_e32 v174, 16, v69
	v_and_b32_e32 v175, 0xffff0000, v69
	v_pk_fma_f32 v[6:7], v[6:7], s[4:5], v[174:175] op_sel_hi:[1,0,1]
	v_lshlrev_b32_e32 v174, 16, v70
	v_and_b32_e32 v175, 0xffff0000, v70
	v_pk_fma_f32 v[8:9], v[8:9], s[4:5], v[174:175] op_sel_hi:[1,0,1]
	v_lshlrev_b32_e32 v174, 16, v71
	v_and_b32_e32 v175, 0xffff0000, v71
	v_pk_fma_f32 v[10:11], v[10:11], s[4:5], v[174:175] op_sel_hi:[1,0,1]
	v_lshlrev_b32_e32 v174, 16, v72
	v_and_b32_e32 v175, 0xffff0000, v72
	v_pk_fma_f32 v[12:13], v[12:13], s[4:5], v[174:175] op_sel_hi:[1,0,1]
	v_lshlrev_b32_e32 v174, 16, v73
	v_and_b32_e32 v175, 0xffff0000, v73
	v_pk_fma_f32 v[14:15], v[14:15], s[4:5], v[174:175] op_sel_hi:[1,0,1]
	v_lshlrev_b32_e32 v174, 16, v74
	v_and_b32_e32 v175, 0xffff0000, v74
	v_pk_fma_f32 v[16:17], v[16:17], s[4:5], v[174:175] op_sel_hi:[1,0,1]
	v_lshlrev_b32_e32 v174, 16, v75
	v_and_b32_e32 v175, 0xffff0000, v75
	v_pk_fma_f32 v[18:19], v[18:19], s[4:5], v[174:175] op_sel_hi:[1,0,1]
	v_lshlrev_b32_e32 v174, 16, v76
	v_and_b32_e32 v175, 0xffff0000, v76
	v_pk_fma_f32 v[20:21], v[20:21], s[4:5], v[174:175] op_sel_hi:[1,0,1]
	v_lshlrev_b32_e32 v174, 16, v77
	v_and_b32_e32 v175, 0xffff0000, v77
	v_pk_fma_f32 v[22:23], v[22:23], s[4:5], v[174:175] op_sel_hi:[1,0,1]
	v_lshlrev_b32_e32 v174, 16, v78
	v_and_b32_e32 v175, 0xffff0000, v78
	v_pk_fma_f32 v[24:25], v[24:25], s[4:5], v[174:175] op_sel_hi:[1,0,1]
	v_lshlrev_b32_e32 v174, 16, v79
	v_and_b32_e32 v175, 0xffff0000, v79
	v_pk_fma_f32 v[26:27], v[26:27], s[4:5], v[174:175] op_sel_hi:[1,0,1]
	v_lshlrev_b32_e32 v174, 16, v80
	v_and_b32_e32 v175, 0xffff0000, v80
	v_pk_fma_f32 v[28:29], v[28:29], s[4:5], v[174:175] op_sel_hi:[1,0,1]
	v_lshlrev_b32_e32 v174, 16, v81
	v_and_b32_e32 v175, 0xffff0000, v81
	v_pk_fma_f32 v[30:31], v[30:31], s[4:5], v[174:175] op_sel_hi:[1,0,1]
	v_lshlrev_b32_e32 v174, 16, v82
	v_and_b32_e32 v175, 0xffff0000, v82
; DI void phase_scan(KArgs args, LAS unsigned char* L, const Ctx& c) {
;     ...
;         SCAN_DMA(); SCAN_DMA(); SCAN_DMA(); SCAN_DMA(); SCAN_DMA();
;         asm volatile("s_waitcnt vmcnt(48)" ::: "memory"); SCAN_LOAD(0);
;         asm volatile("s_waitcnt vmcnt(36)" ::: "memory"); SCAN_LOAD(1);
;         for (int step = 0; step < nch; step += 2) {
;             SCAN_STEP(0, step);     asm volatile("s_waitcnt vmcnt(24)" ::: "memory"); SCAN_LOAD(0); SCAN_DMA();
;             SCAN_STEP(1, step + 1); asm volatile("s_waitcnt vmcnt(24)" ::: "memory"); SCAN_LOAD(1); SCAN_DMA();
	v_pk_fma_f32 v[32:33], v[32:33], s[4:5], v[174:175] op_sel_hi:[1,0,1]
	v_lshlrev_b32_e32 v174, 16, v83
	v_and_b32_e32 v175, 0xffff0000, v83
	v_pk_fma_f32 v[34:35], v[34:35], s[4:5], v[174:175] op_sel_hi:[1,0,1]
	s_nop 1
	v_mfma_f32_32x32x16_bf16 v[4:19], v[36:39], v[132:135], v[4:19]
	v_mfma_f32_32x32x16_bf16 v[20:35], v[52:55], v[132:135], v[20:35]
	v_mfma_f32_32x32x16_bf16 v[4:19], v[40:43], v[136:139], v[4:19]
	v_mfma_f32_32x32x16_bf16 v[20:35], v[56:59], v[136:139], v[20:35]
	v_mfma_f32_32x32x16_bf16 v[4:19], v[44:47], v[140:143], v[4:19]
	v_mfma_f32_32x32x16_bf16 v[20:35], v[60:63], v[140:143], v[20:35]
	v_mfma_f32_32x32x16_bf16 v[4:19], v[48:51], v[144:147], v[4:19]
	v_mfma_f32_32x32x16_bf16 v[20:35], v[64:67], v[144:147], v[20:35]
	v_lshl_add_u64 v[166:167], v[166:167], 0, s[0:1]
	s_add_u32 s14, s12, 0x1000
	s_addc_u32 s15, s13, 0
	s_add_u32 s16, s12, 0x2000
	s_addc_u32 s17, s13, 0
	global_load_dwordx4 v[36:39], v2, s[12:13] nt
	global_load_dwordx4 v[40:43], v2, s[12:13] offset:1024 nt
	global_load_dwordx4 v[44:47], v2, s[12:13] offset:2048 nt
	global_load_dwordx4 v[48:51], v2, s[12:13] offset:3072 nt
	global_load_dwordx4 v[52:55], v2, s[14:15] nt
	global_load_dwordx4 v[56:59], v2, s[14:15] offset:1024 nt
	global_load_dwordx4 v[60:63], v2, s[14:15] offset:2048 nt
	global_load_dwordx4 v[64:67], v2, s[14:15] offset:3072 nt
	global_load_dwordx4 v[68:71], v162, s[16:17] nt
	global_load_dwordx4 v[72:75], v162, s[16:17] offset:16 nt
	global_load_dwordx4 v[76:79], v164, s[16:17] nt
	global_load_dwordx4 v[80:83], v164, s[16:17] offset:16 nt
	s_add_i32 s11, s11, 1
	s_cmp_le_u32 s11, s31
	s_cselect_b32 s6, s0, 0
	s_cselect_b32 s7, s1, 0
	s_add_u32 s12, s12, s6
	s_addc_u32 s13, s13, s7
	s_add_i32 s10, s10, 1
	s_cmp_ge_u32 s10, s30
	s_cbranch_scc1 .Lscan_exit
	s_waitcnt vmcnt(32)
	s_lshr_b32 s6, s10, 6
	s_cmp_lt_u32 s10, 64
	s_cselect_b64 vcc, -1, 0
	s_cmp_eq_u32 s6, 1
	s_cselect_b64 s[4:5], -1, 0
	s_cmp_eq_u32 s6, 2
	s_cselect_b64 s[6:7], -1, 0
	v_cndmask_b32_e64 v172, v170, v169, s[6:7]
	v_cndmask_b32_e64 v172, v172, v168, s[4:5]
	v_cndmask_b32_e32 v172, v172, v1, vcc
	v_cvt_pk_bf16_f32 v132, v4, v5
	v_cvt_pk_bf16_f32 v133, v6, v7
	v_cvt_pk_bf16_f32 v134, v8, v9
	v_cvt_pk_bf16_f32 v135, v10, v11
	v_cvt_pk_bf16_f32 v136, v12, v13
	v_cvt_pk_bf16_f32 v137, v14, v15
	v_cvt_pk_bf16_f32 v138, v16, v17
	v_cvt_pk_bf16_f32 v139, v18, v19
	v_cvt_pk_bf16_f32 v140, v20, v21
	v_cvt_pk_bf16_f32 v141, v22, v23
	v_cvt_pk_bf16_f32 v142, v24, v25
	v_cvt_pk_bf16_f32 v143, v26, v27
	v_cvt_pk_bf16_f32 v144, v28, v29
	v_cvt_pk_bf16_f32 v145, v30, v31
	v_cvt_pk_bf16_f32 v146, v32, v33
	v_cvt_pk_bf16_f32 v147, v34, v35
	v_readlane_b32 s4, v172, s10
	global_store_dwordx4 v[166:167], v[132:135], off offset:-2048 nt
	global_store_dwordx4 v[166:167], v[136:139], off offset:-1024 nt
	global_store_dwordx4 v[166:167], v[140:143], off nt
	global_store_dwordx4 v[166:167], v[144:147], off offset:1024 nt
	v_lshlrev_b32_e32 v174, 16, v116
	v_and_b32_e32 v175, 0xffff0000, v116
	v_pk_fma_f32 v[4:5], v[4:5], s[4:5], v[174:175] op_sel_hi:[1,0,1]
	v_lshlrev_b32_e32 v174, 16, v117
	v_and_b32_e32 v175, 0xffff0000, v117
	v_pk_fma_f32 v[6:7], v[6:7], s[4:5], v[174:175] op_sel_hi:[1,0,1]
	v_lshlrev_b32_e32 v174, 16, v118
	v_and_b32_e32 v175, 0xffff0000, v118
	v_pk_fma_f32 v[8:9], v[8:9], s[4:5], v[174:175] op_sel_hi:[1,0,1]
	v_lshlrev_b32_e32 v174, 16, v119
	v_and_b32_e32 v175, 0xffff0000, v119
	v_pk_fma_f32 v[10:11], v[10:11], s[4:5], v[174:175] op_sel_hi:[1,0,1]
	v_lshlrev_b32_e32 v174, 16, v120
	v_and_b32_e32 v175, 0xffff0000, v120
	v_pk_fma_f32 v[12:13], v[12:13], s[4:5], v[174:175] op_sel_hi:[1,0,1]
	v_lshlrev_b32_e32 v174, 16, v121
	v_and_b32_e32 v175, 0xffff0000, v121
	v_pk_fma_f32 v[14:15], v[14:15], s[4:5], v[174:175] op_sel_hi:[1,0,1]
	v_lshlrev_b32_e32 v174, 16, v122
	v_and_b32_e32 v175, 0xffff0000, v122
	v_pk_fma_f32 v[16:17], v[16:17], s[4:5], v[174:175] op_sel_hi:[1,0,1]
	v_lshlrev_b32_e32 v174, 16, v123
	v_and_b32_e32 v175, 0xffff0000, v123
	v_pk_fma_f32 v[18:19], v[18:19], s[4:5], v[174:175] op_sel_hi:[1,0,1]
	v_lshlrev_b32_e32 v174, 16, v124
	v_and_b32_e32 v175, 0xffff0000, v124
	v_pk_fma_f32 v[20:21], v[20:21], s[4:5], v[174:175] op_sel_hi:[1,0,1]
	v_lshlrev_b32_e32 v174, 16, v125
	v_and_b32_e32 v175, 0xffff0000, v125
	v_pk_fma_f32 v[22:23], v[22:23], s[4:5], v[174:175] op_sel_hi:[1,0,1]
	v_lshlrev_b32_e32 v174, 16, v126
	v_and_b32_e32 v175, 0xffff0000, v126
	v_pk_fma_f32 v[24:25], v[24:25], s[4:5], v[174:175] op_sel_hi:[1,0,1]
	v_lshlrev_b32_e32 v174, 16, v127
	v_and_b32_e32 v175, 0xffff0000, v127
	v_pk_fma_f32 v[26:27], v[26:27], s[4:5], v[174:175] op_sel_hi:[1,0,1]
	v_lshlrev_b32_e32 v174, 16, v128
	v_and_b32_e32 v175, 0xffff0000, v128
	v_pk_fma_f32 v[28:29], v[28:29], s[4:5], v[174:175] op_sel_hi:[1,0,1]
	v_lshlrev_b32_e32 v174, 16, v129
	v_and_b32_e32 v175, 0xffff0000, v129
	v_pk_fma_f32 v[30:31], v[30:31], s[4:5], v[174:175] op_sel_hi:[1,0,1]
	v_lshlrev_b32_e32 v174, 16, v130
	v_and_b32_e32 v175, 0xffff0000, v130
	v_pk_fma_f32 v[32:33], v[32:33], s[4:5], v[174:175] op_sel_hi:[1,0,1]
	v_lshlrev_b32_e32 v174, 16, v131
	v_and_b32_e32 v175, 0xffff0000, v131
	v_pk_fma_f32 v[34:35], v[34:35], s[4:5], v[174:175] op_sel_hi:[1,0,1]
	s_nop 1
	v_mfma_f32_32x32x16_bf16 v[4:19], v[84:87], v[132:135], v[4:19]
	v_mfma_f32_32x32x16_bf16 v[20:35], v[100:103], v[132:135], v[20:35]
	v_mfma_f32_32x32x16_bf16 v[4:19], v[88:91], v[136:139], v[4:19]
	v_mfma_f32_32x32x16_bf16 v[20:35], v[104:107], v[136:139], v[20:35]
	v_mfma_f32_32x32x16_bf16 v[4:19], v[92:95], v[140:143], v[4:19]
	v_mfma_f32_32x32x16_bf16 v[20:35], v[108:111], v[140:143], v[20:35]
	v_mfma_f32_32x32x16_bf16 v[4:19], v[96:99], v[144:147], v[4:19]
	v_mfma_f32_32x32x16_bf16 v[20:35], v[112:115], v[144:147], v[20:35]
	v_lshl_add_u64 v[166:167], v[166:167], 0, s[0:1]
	s_add_u32 s14, s12, 0x1000
	s_addc_u32 s15, s13, 0
	s_add_u32 s16, s12, 0x2000
	s_addc_u32 s17, s13, 0
	global_load_dwordx4 v[84:87], v2, s[12:13] nt
	global_load_dwordx4 v[88:91], v2, s[12:13] offset:1024 nt
	global_load_dwordx4 v[92:95], v2, s[12:13] offset:2048 nt
	global_load_dwordx4 v[96:99], v2, s[12:13] offset:3072 nt
	global_load_dwordx4 v[100:103], v2, s[14:15] nt
	global_load_dwordx4 v[104:107], v2, s[14:15] offset:1024 nt
	global_load_dwordx4 v[108:111], v2, s[14:15] offset:2048 nt
	global_load_dwordx4 v[112:115], v2, s[14:15] offset:3072 nt
	global_load_dwordx4 v[116:119], v162, s[16:17] nt
	global_load_dwordx4 v[120:123], v162, s[16:17] offset:16 nt
	global_load_dwordx4 v[124:127], v164, s[16:17] nt
	global_load_dwordx4 v[128:131], v164, s[16:17] offset:16 nt
	s_add_i32 s11, s11, 1
	s_cmp_le_u32 s11, s31
	s_cselect_b32 s6, s0, 0
	s_cselect_b32 s7, s1, 0
	s_add_u32 s12, s12, s6
	s_addc_u32 s13, s13, s7
	s_add_i32 s10, s10, 1
	s_cmp_ge_u32 s10, s30
	s_cbranch_scc1 .Lscan_exit
; DI void phase_scan(KArgs args, LAS unsigned char* L, const Ctx& c) {
;     ...
;         SCAN_DMA(); SCAN_DMA(); SCAN_DMA(); SCAN_DMA(); SCAN_DMA();
;         asm volatile("s_waitcnt vmcnt(48)" ::: "memory"); SCAN_LOAD(0);
;         asm volatile("s_waitcnt vmcnt(36)" ::: "memory"); SCAN_LOAD(1);
;         for (int step = 0; step < nch; step += 2) {
;             SCAN_STEP(0, step);     asm volatile("s_waitcnt vmcnt(24)" ::: "memory"); SCAN_LOAD(0); SCAN_DMA();
;             SCAN_STEP(1, step + 1); asm volatile("s_waitcnt vmcnt(24)" ::: "memory"); SCAN_LOAD(1); SCAN_DMA();
	s_waitcnt vmcnt(32)
	s_lshr_b32 s6, s10, 6
	s_cmp_lt_u32 s10, 64
	s_cselect_b64 vcc, -1, 0
	s_cmp_eq_u32 s6, 1
	s_cselect_b64 s[4:5], -1, 0
	s_cmp_eq_u32 s6, 2
	s_cselect_b64 s[6:7], -1, 0
	v_cndmask_b32_e64 v172, v170, v169, s[6:7]
	v_cndmask_b32_e64 v172, v172, v168, s[4:5]
	v_cndmask_b32_e32 v172, v172, v1, vcc
	v_cvt_pk_bf16_f32 v132, v4, v5
	v_cvt_pk_bf16_f32 v133, v6, v7
	v_cvt_pk_bf16_f32 v134, v8, v9
	v_cvt_pk_bf16_f32 v135, v10, v11
	v_cvt_pk_bf16_f32 v136, v12, v13
	v_cvt_pk_bf16_f32 v137, v14, v15
	v_cvt_pk_bf16_f32 v138, v16, v17
	v_cvt_pk_bf16_f32 v139, v18, v19
	v_cvt_pk_bf16_f32 v140, v20, v21
	v_cvt_pk_bf16_f32 v141, v22, v23
	v_cvt_pk_bf16_f32 v142, v24, v25
	v_cvt_pk_bf16_f32 v143, v26, v27
	v_cvt_pk_bf16_f32 v144, v28, v29
	v_cvt_pk_bf16_f32 v145, v30, v31
	v_cvt_pk_bf16_f32 v146, v32, v33
	v_cvt_pk_bf16_f32 v147, v34, v35
	v_readlane_b32 s4, v172, s10
	global_store_dwordx4 v[166:167], v[132:135], off offset:-2048 nt
	global_store_dwordx4 v[166:167], v[136:139], off offset:-1024 nt
	global_store_dwordx4 v[166:167], v[140:143], off nt
	global_store_dwordx4 v[166:167], v[144:147], off offset:1024 nt
	v_lshlrev_b32_e32 v174, 16, v230
	v_and_b32_e32 v175, 0xffff0000, v230
	v_pk_fma_f32 v[4:5], v[4:5], s[4:5], v[174:175] op_sel_hi:[1,0,1]
	v_lshlrev_b32_e32 v174, 16, v231
	v_and_b32_e32 v175, 0xffff0000, v231
	v_pk_fma_f32 v[6:7], v[6:7], s[4:5], v[174:175] op_sel_hi:[1,0,1]
	v_lshlrev_b32_e32 v174, 16, v232
	v_and_b32_e32 v175, 0xffff0000, v232
	v_pk_fma_f32 v[8:9], v[8:9], s[4:5], v[174:175] op_sel_hi:[1,0,1]
	v_lshlrev_b32_e32 v174, 16, v233
	v_and_b32_e32 v175, 0xffff0000, v233
	v_pk_fma_f32 v[10:11], v[10:11], s[4:5], v[174:175] op_sel_hi:[1,0,1]
	v_lshlrev_b32_e32 v174, 16, v234
	v_and_b32_e32 v175, 0xffff0000, v234
	v_pk_fma_f32 v[12:13], v[12:13], s[4:5], v[174:175] op_sel_hi:[1,0,1]
	v_lshlrev_b32_e32 v174, 16, v235
	v_and_b32_e32 v175, 0xffff0000, v235
	v_pk_fma_f32 v[14:15], v[14:15], s[4:5], v[174:175] op_sel_hi:[1,0,1]
	v_lshlrev_b32_e32 v174, 16, v236
	v_and_b32_e32 v175, 0xffff0000, v236
	v_pk_fma_f32 v[16:17], v[16:17], s[4:5], v[174:175] op_sel_hi:[1,0,1]
	v_lshlrev_b32_e32 v174, 16, v237
	v_and_b32_e32 v175, 0xffff0000, v237
	v_pk_fma_f32 v[18:19], v[18:19], s[4:5], v[174:175] op_sel_hi:[1,0,1]
	v_lshlrev_b32_e32 v174, 16, v238
	v_and_b32_e32 v175, 0xffff0000, v238
	v_pk_fma_f32 v[20:21], v[20:21], s[4:5], v[174:175] op_sel_hi:[1,0,1]
	v_lshlrev_b32_e32 v174, 16, v239
	v_and_b32_e32 v175, 0xffff0000, v239
	v_pk_fma_f32 v[22:23], v[22:23], s[4:5], v[174:175] op_sel_hi:[1,0,1]
	v_lshlrev_b32_e32 v174, 16, v240
	v_and_b32_e32 v175, 0xffff0000, v240
	v_pk_fma_f32 v[24:25], v[24:25], s[4:5], v[174:175] op_sel_hi:[1,0,1]
	v_lshlrev_b32_e32 v174, 16, v241
	v_and_b32_e32 v175, 0xffff0000, v241
	v_pk_fma_f32 v[26:27], v[26:27], s[4:5], v[174:175] op_sel_hi:[1,0,1]
	v_lshlrev_b32_e32 v174, 16, v242
	v_and_b32_e32 v175, 0xffff0000, v242
	v_pk_fma_f32 v[28:29], v[28:29], s[4:5], v[174:175] op_sel_hi:[1,0,1]
	v_lshlrev_b32_e32 v174, 16, v243
	v_and_b32_e32 v175, 0xffff0000, v243
	v_pk_fma_f32 v[30:31], v[30:31], s[4:5], v[174:175] op_sel_hi:[1,0,1]
	v_lshlrev_b32_e32 v174, 16, v244
	v_and_b32_e32 v175, 0xffff0000, v244
	v_pk_fma_f32 v[32:33], v[32:33], s[4:5], v[174:175] op_sel_hi:[1,0,1]
	v_lshlrev_b32_e32 v174, 16, v245
	v_and_b32_e32 v175, 0xffff0000, v245
	v_pk_fma_f32 v[34:35], v[34:35], s[4:5], v[174:175] op_sel_hi:[1,0,1]
	s_nop 1
	v_mfma_f32_32x32x16_bf16 v[4:19], v[178:181], v[132:135], v[4:19]
	v_mfma_f32_32x32x16_bf16 v[20:35], v[194:197], v[132:135], v[20:35]
	v_mfma_f32_32x32x16_bf16 v[4:19], v[182:185], v[136:139], v[4:19]
	v_mfma_f32_32x32x16_bf16 v[20:35], v[198:201], v[136:139], v[20:35]
	v_mfma_f32_32x32x16_bf16 v[4:19], v[186:189], v[140:143], v[4:19]
	v_mfma_f32_32x32x16_bf16 v[20:35], v[202:205], v[140:143], v[20:35]
	v_mfma_f32_32x32x16_bf16 v[4:19], v[190:193], v[144:147], v[4:19]
	v_mfma_f32_32x32x16_bf16 v[20:35], v[226:229], v[144:147], v[20:35]
	v_lshl_add_u64 v[166:167], v[166:167], 0, s[0:1]
	s_add_u32 s14, s12, 0x1000
	s_addc_u32 s15, s13, 0
	s_add_u32 s16, s12, 0x2000
	s_addc_u32 s17, s13, 0
	global_load_dwordx4 v[178:181], v2, s[12:13] nt
	global_load_dwordx4 v[182:185], v2, s[12:13] offset:1024 nt
	global_load_dwordx4 v[186:189], v2, s[12:13] offset:2048 nt
	global_load_dwordx4 v[190:193], v2, s[12:13] offset:3072 nt
	global_load_dwordx4 v[194:197], v2, s[14:15] nt
	global_load_dwordx4 v[198:201], v2, s[14:15] offset:1024 nt
	global_load_dwordx4 v[202:205], v2, s[14:15] offset:2048 nt
	global_load_dwordx4 v[226:229], v2, s[14:15] offset:3072 nt
	global_load_dwordx4 v[230:233], v162, s[16:17] nt
	global_load_dwordx4 v[234:237], v162, s[16:17] offset:16 nt
	global_load_dwordx4 v[238:241], v164, s[16:17] nt
	global_load_dwordx4 v[242:245], v164, s[16:17] offset:16 nt
	s_add_i32 s11, s11, 1
	s_cmp_le_u32 s11, s31
	s_cselect_b32 s6, s0, 0
	s_cselect_b32 s7, s1, 0
	s_add_u32 s12, s12, s6
	s_addc_u32 s13, s13, s7
	s_add_i32 s10, s10, 1
	s_cmp_ge_u32 s10, s30
	s_cbranch_scc1 .Lscan_exit
	s_branch .Lscan_loop
